# pe-bias partial sums (workgroups 0-31, critical path of the merged LN3+prep_weights phase): all 64 products loaded in one batch instead of four waited batches
# baseline (speedup 1.0000x reference)
; __device__ __forceinline__ void prep_weights(lptr L, const Params& P, int l) {
;     ...
;     if (blockIdx.x < 32) {
;         const int src = blockIdx.x >> 4, part = (blockIdx.x & 15) * 2 + (tid >> 8), n = tid & 255;
;         const float* pe = (src ? P.in[8] : P.in[7]) + (size_t)l * 2048; const float* w1 = (src ? P.in[11] : P.in[9]) + (size_t)l * 2048 * 256;
;         float s = 0.f;
;         for (int k = 64 * part; k < 64 * part + 64; ++k) s += pe[k] * w1[(size_t)k * 256 + n];
;         ((float*)(ws + W_PEB))[(src * 32 + part) * 256 + n] = s;
;     }
.LBB0_939:
	s_mov_b64 s[2:3], 0x1000
	global_load_dwordx4 v[20:23], v[2:3], off
	global_load_dwordx4 v[24:27], v[2:3], off offset:16
	global_load_dwordx4 v[28:31], v[2:3], off offset:32
	global_load_dwordx4 v[32:35], v[2:3], off offset:48
	global_load_dwordx4 v[36:39], v[2:3], off offset:64
	global_load_dwordx4 v[40:43], v[2:3], off offset:80
	global_load_dwordx4 v[44:47], v[2:3], off offset:96
	global_load_dwordx4 v[48:51], v[2:3], off offset:112
	global_load_dwordx4 v[52:55], v[2:3], off offset:128
	global_load_dwordx4 v[56:59], v[2:3], off offset:144
	global_load_dwordx4 v[60:63], v[2:3], off offset:160
	global_load_dwordx4 v[64:67], v[2:3], off offset:176
	global_load_dwordx4 v[68:71], v[2:3], off offset:192
	global_load_dwordx4 v[72:75], v[2:3], off offset:208
	global_load_dwordx4 v[76:79], v[2:3], off offset:224
	global_load_dwordx4 v[80:83], v[2:3], off offset:240
	global_load_dword v84, v[4:5], off
	global_load_dword v85, v[4:5], off offset:1024
	global_load_dword v86, v[4:5], off offset:2048
	global_load_dword v87, v[4:5], off offset:3072
	v_lshl_add_u64 v[4:5], v[4:5], 0, s[2:3]
	global_load_dword v88, v[4:5], off
	global_load_dword v89, v[4:5], off offset:1024
	global_load_dword v90, v[4:5], off offset:2048
	global_load_dword v91, v[4:5], off offset:3072
	v_lshl_add_u64 v[4:5], v[4:5], 0, s[2:3]
	global_load_dword v92, v[4:5], off
	global_load_dword v93, v[4:5], off offset:1024
	global_load_dword v94, v[4:5], off offset:2048
	global_load_dword v95, v[4:5], off offset:3072
	v_lshl_add_u64 v[4:5], v[4:5], 0, s[2:3]
	global_load_dword v96, v[4:5], off
	global_load_dword v97, v[4:5], off offset:1024
	global_load_dword v98, v[4:5], off offset:2048
	global_load_dword v99, v[4:5], off offset:3072
	v_lshl_add_u64 v[4:5], v[4:5], 0, s[2:3]
	global_load_dword v100, v[4:5], off
	global_load_dword v101, v[4:5], off offset:1024
	global_load_dword v102, v[4:5], off offset:2048
	global_load_dword v103, v[4:5], off offset:3072
	v_lshl_add_u64 v[4:5], v[4:5], 0, s[2:3]
	global_load_dword v104, v[4:5], off
	global_load_dword v105, v[4:5], off offset:1024
	global_load_dword v106, v[4:5], off offset:2048
	global_load_dword v107, v[4:5], off offset:3072
	v_lshl_add_u64 v[4:5], v[4:5], 0, s[2:3]
	global_load_dword v108, v[4:5], off
	global_load_dword v109, v[4:5], off offset:1024
	global_load_dword v110, v[4:5], off offset:2048
	global_load_dword v111, v[4:5], off offset:3072
	v_lshl_add_u64 v[4:5], v[4:5], 0, s[2:3]
	global_load_dword v112, v[4:5], off
	global_load_dword v113, v[4:5], off offset:1024
	global_load_dword v114, v[4:5], off offset:2048
	global_load_dword v115, v[4:5], off offset:3072
	v_lshl_add_u64 v[4:5], v[4:5], 0, s[2:3]
	global_load_dword v116, v[4:5], off
	global_load_dword v117, v[4:5], off offset:1024
	global_load_dword v118, v[4:5], off offset:2048
	global_load_dword v119, v[4:5], off offset:3072
	v_lshl_add_u64 v[4:5], v[4:5], 0, s[2:3]
	global_load_dword v120, v[4:5], off
	global_load_dword v121, v[4:5], off offset:1024
	global_load_dword v122, v[4:5], off offset:2048
	global_load_dword v123, v[4:5], off offset:3072
	v_lshl_add_u64 v[4:5], v[4:5], 0, s[2:3]
	global_load_dword v124, v[4:5], off
	global_load_dword v125, v[4:5], off offset:1024
	global_load_dword v126, v[4:5], off offset:2048
	global_load_dword v127, v[4:5], off offset:3072
	v_lshl_add_u64 v[4:5], v[4:5], 0, s[2:3]
	global_load_dword v128, v[4:5], off
	global_load_dword v129, v[4:5], off offset:1024
	global_load_dword v130, v[4:5], off offset:2048
	global_load_dword v131, v[4:5], off offset:3072
	v_lshl_add_u64 v[4:5], v[4:5], 0, s[2:3]
	global_load_dword v132, v[4:5], off
	global_load_dword v133, v[4:5], off offset:1024
	global_load_dword v134, v[4:5], off offset:2048
	global_load_dword v135, v[4:5], off offset:3072
	v_lshl_add_u64 v[4:5], v[4:5], 0, s[2:3]
	global_load_dword v136, v[4:5], off
	global_load_dword v137, v[4:5], off offset:1024
	global_load_dword v138, v[4:5], off offset:2048
	global_load_dword v139, v[4:5], off offset:3072
	v_lshl_add_u64 v[4:5], v[4:5], 0, s[2:3]
	global_load_dword v140, v[4:5], off
	global_load_dword v141, v[4:5], off offset:1024
	global_load_dword v142, v[4:5], off offset:2048
	global_load_dword v143, v[4:5], off offset:3072
	v_lshl_add_u64 v[4:5], v[4:5], 0, s[2:3]
	global_load_dword v144, v[4:5], off
	global_load_dword v145, v[4:5], off offset:1024
	global_load_dword v146, v[4:5], off offset:2048
	global_load_dword v147, v[4:5], off offset:3072
	s_waitcnt vmcnt(0)
	v_fmac_f32_e32 v9, v20, v84
	v_fmac_f32_e32 v9, v21, v85
	v_fmac_f32_e32 v9, v22, v86
	v_fmac_f32_e32 v9, v23, v87
	v_fmac_f32_e32 v9, v24, v88
	v_fmac_f32_e32 v9, v25, v89
	v_fmac_f32_e32 v9, v26, v90
	v_fmac_f32_e32 v9, v27, v91
	v_fmac_f32_e32 v9, v28, v92
	v_fmac_f32_e32 v9, v29, v93
	v_fmac_f32_e32 v9, v30, v94
	v_fmac_f32_e32 v9, v31, v95
	v_fmac_f32_e32 v9, v32, v96
	v_fmac_f32_e32 v9, v33, v97
	v_fmac_f32_e32 v9, v34, v98
	v_fmac_f32_e32 v9, v35, v99
	v_fmac_f32_e32 v9, v36, v100
	v_fmac_f32_e32 v9, v37, v101
	v_fmac_f32_e32 v9, v38, v102
	v_fmac_f32_e32 v9, v39, v103
	v_fmac_f32_e32 v9, v40, v104
	v_fmac_f32_e32 v9, v41, v105
	v_fmac_f32_e32 v9, v42, v106
	v_fmac_f32_e32 v9, v43, v107
	v_fmac_f32_e32 v9, v44, v108
	v_fmac_f32_e32 v9, v45, v109
	v_fmac_f32_e32 v9, v46, v110
	v_fmac_f32_e32 v9, v47, v111
	v_fmac_f32_e32 v9, v48, v112
	v_fmac_f32_e32 v9, v49, v113
	v_fmac_f32_e32 v9, v50, v114
	v_fmac_f32_e32 v9, v51, v115
	v_fmac_f32_e32 v9, v52, v116
	v_fmac_f32_e32 v9, v53, v117
	v_fmac_f32_e32 v9, v54, v118
	v_fmac_f32_e32 v9, v55, v119
	v_fmac_f32_e32 v9, v56, v120
	v_fmac_f32_e32 v9, v57, v121
	v_fmac_f32_e32 v9, v58, v122
	v_fmac_f32_e32 v9, v59, v123
	v_fmac_f32_e32 v9, v60, v124
	v_fmac_f32_e32 v9, v61, v125
	v_fmac_f32_e32 v9, v62, v126
	v_fmac_f32_e32 v9, v63, v127
	v_fmac_f32_e32 v9, v64, v128
	v_fmac_f32_e32 v9, v65, v129
	v_fmac_f32_e32 v9, v66, v130
	v_fmac_f32_e32 v9, v67, v131
	v_fmac_f32_e32 v9, v68, v132
	v_fmac_f32_e32 v9, v69, v133
	v_fmac_f32_e32 v9, v70, v134
	v_fmac_f32_e32 v9, v71, v135
	v_fmac_f32_e32 v9, v72, v136
	v_fmac_f32_e32 v9, v73, v137
	v_fmac_f32_e32 v9, v74, v138
	v_fmac_f32_e32 v9, v75, v139
	v_fmac_f32_e32 v9, v76, v140
	v_fmac_f32_e32 v9, v77, v141
	v_fmac_f32_e32 v9, v78, v142
	v_fmac_f32_e32 v9, v79, v143
	v_fmac_f32_e32 v9, v80, v144
	v_fmac_f32_e32 v9, v81, v145
	v_fmac_f32_e32 v9, v82, v146
	v_fmac_f32_e32 v9, v83, v147
	s_or_b64 exec, exec, s[0:1]
	v_readlane_b32 s0, v253, 28
	s_nop 1
	v_add_u32_e32 v0, s0, v0
	v_lshl_or_b32 v2, v0, 8, v6
	v_readlane_b32 s0, v253, 26
	v_ashrrev_i32_e32 v3, 31, v2
	v_readlane_b32 s1, v253, 27
	s_nop 1
	v_lshl_add_u64 v[2:3], v[2:3], 2, s[0:1]
	global_store_dword v[2:3], v9, off
